# staggered small/big GEMM order in four phases plus software-pipelined residual loads in the P5 epilogue
# speedup vs baseline: 1.0006x; 1.0006x over previous
.LBB0_480:
	s_cmp_lt_i32 s42, 32
	s_cselect_b32 s47, s13, s15
	s_cselect_b32 s46, s12, s14
	s_lshl_b32 s35, s42, 8
	v_add_u32_e32 v182, s35, v153
	v_lshl_or_b32 v180, s44, 8, v158
	v_ashrrev_i32_e32 v183, 31, v182
	v_ashrrev_i32_e32 v181, 31, v180
	v_lshlrev_b64 v[184:185], 11, v[182:183]
	v_lshl_add_u64 v[188:189], v[184:185], 0, v[180:181]
	v_lshl_add_u64 v[186:187], v[188:189], 2, s[46:47]
	global_load_dwordx4 v[192:195], v[186:187], off
	global_load_dwordx4 v[196:199], v[186:187], off offset:16
	global_load_dwordx4 v[200:203], v[186:187], off offset:512
	global_load_dwordx4 v[204:207], v[186:187], off offset:528
	v_add_u32_e32 v186, s35, v155
	v_ashrrev_i32_e32 v187, 31, v186
	v_lshlrev_b64 v[190:191], 11, v[186:187]
	v_lshl_add_u64 v[184:185], v[190:191], 0, v[180:181]
	v_lshl_add_u64 v[208:209], v[184:185], 2, s[46:47]
	global_load_dwordx4 v[210:213], v[208:209], off
	global_load_dwordx4 v[216:219], v[208:209], off offset:16
	global_load_dwordx4 v[222:225], v[208:209], off offset:512
	global_load_dwordx4 v[226:229], v[208:209], off offset:528
	v_lshl_add_u64 v[172:173], v[188:189], 1, s[16:17]
	v_xor_b32_e32 v163, 32, v162
	s_waitcnt vmcnt(7)
	v_pk_fma_f32 v[128:129], v[194:195], s[30:31], v[128:129] op_sel_hi:[1,0,1]
	v_pk_fma_f32 v[176:177], v[192:193], s[30:31], v[126:127] op_sel_hi:[1,0,1]
	s_waitcnt vmcnt(6)
	v_pk_fma_f32 v[170:171], v[198:199], s[30:31], v[124:125] op_sel_hi:[1,0,1]
	v_pk_fma_f32 v[168:169], v[196:197], s[30:31], v[122:123] op_sel_hi:[1,0,1]
	v_cvt_pk_bf16_f32 v122, v176, v177
	v_cvt_pk_bf16_f32 v123, v128, v129
	v_add_f32_e32 v178, v170, v171
	v_cvt_pk_bf16_f32 v124, v168, v169
	v_cvt_pk_bf16_f32 v125, v170, v171
	global_store_dwordx4 v[172:173], v[122:125], off
	s_nop 0
	s_nop 0
	s_nop 0
	v_and_b32_e32 v123, 64, v162
	v_xor_b32_e32 v122, 16, v162
	v_add_u32_e32 v123, 64, v123
	v_cmp_lt_i32_e32 vcc, v122, v123
	v_add_f32_e32 v174, v128, v129
	v_add_f32_e32 v175, v168, v169
	v_cndmask_b32_e32 v122, v162, v122, vcc
	v_cmp_lt_i32_e32 vcc, v163, v123
	v_mul_f32_e32 v129, v129, v129
	v_mul_f32_e32 v169, v169, v169
	v_cndmask_b32_e32 v123, v162, v163, vcc
	v_add_f32_e32 v163, v176, v177
	v_mul_f32_e32 v177, v177, v177
	v_mul_f32_e32 v171, v171, v171
	v_add_f32_e32 v163, v163, v174
	v_add_f32_e32 v174, v175, v178
	v_fmac_f32_e32 v177, v176, v176
	v_fmac_f32_e32 v129, v128, v128
	v_fmac_f32_e32 v169, v168, v168
	v_fmac_f32_e32 v171, v170, v170
	v_add_f32_e32 v128, v163, v174
	v_add_f32_e32 v129, v177, v129
	v_add_f32_e32 v163, v169, v171
	v_add_f32_e32 v168, 0, v128
	v_add_f32_e32 v163, v129, v163
	v_lshlrev_b32_e32 v122, 2, v122
	s_waitcnt vmcnt(6)
	v_pk_fma_f32 v[120:121], v[202:203], s[30:31], v[120:121] op_sel_hi:[1,0,1]
	v_pk_fma_f32 v[118:119], v[200:201], s[30:31], v[118:119] op_sel_hi:[1,0,1]
	s_waitcnt vmcnt(5)
	v_pk_fma_f32 v[128:129], v[206:207], s[30:31], v[116:117] op_sel_hi:[1,0,1]
	v_pk_fma_f32 v[126:127], v[204:205], s[30:31], v[114:115] op_sel_hi:[1,0,1]
	v_add_f32_e32 v114, v118, v119
	v_add_f32_e32 v115, v120, v121
	v_add_f32_e32 v116, v126, v127
	v_add_f32_e32 v117, v128, v129
	v_mul_f32_e32 v124, v119, v119
	v_mul_f32_e32 v125, v121, v121
	v_mul_f32_e32 v164, v127, v127
	v_mul_f32_e32 v165, v129, v129
	v_add_f32_e32 v114, v114, v115
	v_add_f32_e32 v115, v116, v117
	v_fmac_f32_e32 v124, v118, v118
	v_fmac_f32_e32 v125, v120, v120
	v_fmac_f32_e32 v164, v126, v126
	v_fmac_f32_e32 v165, v128, v128
	v_add_f32_e32 v114, v114, v115
	v_add_f32_e32 v115, v124, v125
	v_add_f32_e32 v116, v164, v165
	v_add_f32_e32 v115, v115, v116
	v_add_f32_e32 v114, v168, v114
	v_add_f32_e32 v125, v163, v115
	ds_bpermute_b32 v117, v122, v114
	ds_bpermute_b32 v163, v122, v125
	v_lshlrev_b32_e32 v116, 2, v123
	v_cvt_pk_bf16_f32 v124, v118, v119
	s_waitcnt lgkmcnt(1)
	v_add_f32_e32 v114, v114, v117
	s_waitcnt lgkmcnt(0)
	v_add_f32_e32 v117, v125, v163
	ds_bpermute_b32 v115, v116, v114
	ds_bpermute_b32 v118, v116, v117
	v_cvt_pk_bf16_f32 v125, v120, v121
	v_cvt_pk_bf16_f32 v126, v126, v127
	v_cvt_pk_bf16_f32 v127, v128, v129
	global_store_dwordx4 v[172:173], v[124:127], off offset:256
	s_and_saveexec_b64 s[42:43], s[6:7]
	s_waitcnt lgkmcnt(1)
	v_add_f32_e32 v114, v114, v115
	s_waitcnt lgkmcnt(0)
	v_add_f32_e32 v115, v117, v118
	v_lshl_add_u64 v[120:121], v[182:183], 3, v[138:139]
	v_cndmask_b32_e64 v114, v115, v114, s[8:9]
	global_atomic_add_f32 v[120:121], v114, off
.LBB0_482:
	s_or_b64 exec, exec, s[42:43]
	v_add_u32_e32 v190, s35, v156
	v_ashrrev_i32_e32 v191, 31, v190
	v_lshlrev_b64 v[188:189], 11, v[190:191]
	v_lshl_add_u64 v[192:193], v[188:189], 0, v[180:181]
	v_lshl_add_u64 v[194:195], v[192:193], 2, s[46:47]
	global_load_dwordx4 v[196:199], v[194:195], off
	global_load_dwordx4 v[200:203], v[194:195], off offset:16
	global_load_dwordx4 v[206:209], v[194:195], off offset:512
	global_load_dwordx4 v[230:233], v[194:195], off offset:528
	s_waitcnt lgkmcnt(1)
	s_waitcnt lgkmcnt(0)
	v_lshl_add_u64 v[128:129], v[184:185], 1, s[16:17]
	s_waitcnt vmcnt(10)
	v_pk_fma_f32 v[120:121], v[212:213], s[30:31], v[112:113] op_sel_hi:[1,0,1]
	v_pk_fma_f32 v[118:119], v[210:211], s[30:31], v[110:111] op_sel_hi:[1,0,1]
	s_waitcnt vmcnt(9)
	v_pk_fma_f32 v[126:127], v[218:219], s[30:31], v[108:109] op_sel_hi:[1,0,1]
	v_pk_fma_f32 v[124:125], v[216:217], s[30:31], v[106:107] op_sel_hi:[1,0,1]
	v_cvt_pk_bf16_f32 v106, v118, v119
	v_cvt_pk_bf16_f32 v107, v120, v121
	v_add_f32_e32 v117, v118, v119
	v_cvt_pk_bf16_f32 v108, v124, v125
	v_cvt_pk_bf16_f32 v109, v126, v127
	global_store_dwordx4 v[128:129], v[106:109], off
	s_nop 0
	s_nop 0
	s_nop 0
	v_add_f32_e32 v123, v120, v121
	v_add_f32_e32 v151, v124, v125
	v_add_f32_e32 v163, v126, v127
	v_mul_f32_e32 v119, v119, v119
	v_mul_f32_e32 v121, v121, v121
	v_mul_f32_e32 v125, v125, v125
	v_mul_f32_e32 v127, v127, v127
	v_add_f32_e32 v117, v117, v123
	v_add_f32_e32 v123, v151, v163
	v_fmac_f32_e32 v119, v118, v118
	v_fmac_f32_e32 v121, v120, v120
	v_fmac_f32_e32 v125, v124, v124
	v_fmac_f32_e32 v127, v126, v126
	v_add_f32_e32 v117, v117, v123
	v_add_f32_e32 v118, v119, v121
	v_add_f32_e32 v119, v125, v127
	v_add_f32_e32 v117, 0, v117
	v_add_f32_e32 v118, v118, v119
	s_waitcnt vmcnt(9)
	v_pk_fma_f32 v[104:105], v[224:225], s[30:31], v[104:105] op_sel_hi:[1,0,1]
	v_pk_fma_f32 v[102:103], v[222:223], s[30:31], v[102:103] op_sel_hi:[1,0,1]
	s_waitcnt vmcnt(8)
	v_pk_fma_f32 v[106:107], v[228:229], s[30:31], v[100:101] op_sel_hi:[1,0,1]
	v_pk_fma_f32 v[108:109], v[226:227], s[30:31], v[98:99] op_sel_hi:[1,0,1]
	v_add_f32_e32 v98, v102, v103
	v_add_f32_e32 v99, v104, v105
	v_add_f32_e32 v100, v108, v109
	v_add_f32_e32 v101, v106, v107
	v_mul_f32_e32 v110, v103, v103
	v_mul_f32_e32 v111, v105, v105
	v_mul_f32_e32 v112, v109, v109
	v_mul_f32_e32 v113, v107, v107
	v_add_f32_e32 v98, v98, v99
	v_add_f32_e32 v99, v100, v101
	v_fmac_f32_e32 v110, v102, v102
	v_fmac_f32_e32 v111, v104, v104
	v_fmac_f32_e32 v112, v108, v108
	v_fmac_f32_e32 v113, v106, v106
	v_add_f32_e32 v98, v98, v99
	v_add_f32_e32 v99, v110, v111
	v_add_f32_e32 v100, v112, v113
	v_add_f32_e32 v99, v99, v100
	v_add_f32_e32 v98, v117, v98
	v_add_f32_e32 v101, v118, v99
	ds_bpermute_b32 v100, v122, v98
	ds_bpermute_b32 v110, v122, v101
	v_cvt_pk_bf16_f32 v102, v102, v103
	v_cvt_pk_bf16_f32 v103, v104, v105
	v_cvt_pk_bf16_f32 v104, v108, v109
	s_waitcnt lgkmcnt(1)
	v_add_f32_e32 v98, v98, v100
	s_waitcnt lgkmcnt(0)
	v_add_f32_e32 v100, v101, v110
	ds_bpermute_b32 v99, v116, v98
	ds_bpermute_b32 v101, v116, v100
	v_cvt_pk_bf16_f32 v105, v106, v107
	global_store_dwordx4 v[128:129], v[102:105], off offset:256
	s_and_saveexec_b64 s[42:43], s[6:7]
	s_waitcnt lgkmcnt(1)
	v_add_f32_e32 v98, v98, v99
	s_waitcnt lgkmcnt(0)
	v_add_f32_e32 v99, v100, v101
	v_lshl_add_u64 v[102:103], v[186:187], 3, v[138:139]
	v_cndmask_b32_e64 v98, v99, v98, s[8:9]
	global_atomic_add_f32 v[102:103], v98, off
.LBB0_484:
	s_or_b64 exec, exec, s[42:43]
	v_add_u32_e32 v186, s35, v157
	v_ashrrev_i32_e32 v187, 31, v186
	v_lshlrev_b64 v[184:185], 11, v[186:187]
	v_lshl_add_u64 v[188:189], v[184:185], 0, v[180:181]
	v_lshl_add_u64 v[194:195], v[188:189], 2, s[46:47]
	global_load_dwordx4 v[212:215], v[194:195], off
	global_load_dwordx4 v[216:219], v[194:195], off offset:16
	global_load_dwordx4 v[222:225], v[194:195], off offset:512
	global_load_dwordx4 v[226:229], v[194:195], off offset:528
	s_waitcnt lgkmcnt(1)
	s_waitcnt lgkmcnt(0)
	v_lshl_add_u64 v[108:109], v[192:193], 1, s[16:17]
	s_waitcnt vmcnt(10)
	v_pk_fma_f32 v[102:103], v[198:199], s[30:31], v[96:97] op_sel_hi:[1,0,1]
	v_pk_fma_f32 v[100:101], v[196:197], s[30:31], v[94:95] op_sel_hi:[1,0,1]
	s_waitcnt vmcnt(9)
	v_pk_fma_f32 v[106:107], v[202:203], s[30:31], v[92:93] op_sel_hi:[1,0,1]
	v_pk_fma_f32 v[104:105], v[200:201], s[30:31], v[90:91] op_sel_hi:[1,0,1]
	v_cvt_pk_bf16_f32 v90, v100, v101
	v_cvt_pk_bf16_f32 v91, v102, v103
	v_add_f32_e32 v113, v106, v107
	v_cvt_pk_bf16_f32 v92, v104, v105
	v_cvt_pk_bf16_f32 v93, v106, v107
	global_store_dwordx4 v[108:109], v[90:93], off
	s_nop 0
	s_nop 0
	s_nop 0
	v_add_f32_e32 v110, v100, v101
	v_add_f32_e32 v111, v102, v103
	v_add_f32_e32 v112, v104, v105
	v_mul_f32_e32 v101, v101, v101
	v_mul_f32_e32 v103, v103, v103
	v_mul_f32_e32 v105, v105, v105
	v_mul_f32_e32 v107, v107, v107
	v_add_f32_e32 v110, v110, v111
	v_add_f32_e32 v111, v112, v113
	v_fmac_f32_e32 v101, v100, v100
	v_fmac_f32_e32 v103, v102, v102
	v_fmac_f32_e32 v105, v104, v104
	v_fmac_f32_e32 v107, v106, v106
	v_add_f32_e32 v100, v110, v111
	v_add_f32_e32 v101, v101, v103
	v_add_f32_e32 v102, v105, v107
	v_add_f32_e32 v100, 0, v100
	v_add_f32_e32 v101, v101, v102
	s_waitcnt vmcnt(9)
	v_pk_fma_f32 v[88:89], v[208:209], s[30:31], v[88:89] op_sel_hi:[1,0,1]
	v_pk_fma_f32 v[86:87], v[206:207], s[30:31], v[86:87] op_sel_hi:[1,0,1]
	s_waitcnt vmcnt(8)
	v_pk_fma_f32 v[90:91], v[232:233], s[30:31], v[84:85] op_sel_hi:[1,0,1]
	v_pk_fma_f32 v[92:93], v[230:231], s[30:31], v[82:83] op_sel_hi:[1,0,1]
	v_add_f32_e32 v82, v86, v87
	v_add_f32_e32 v83, v88, v89
	v_add_f32_e32 v84, v92, v93
	v_add_f32_e32 v85, v90, v91
	v_mul_f32_e32 v94, v87, v87
	v_mul_f32_e32 v95, v89, v89
	v_mul_f32_e32 v96, v93, v93
	v_mul_f32_e32 v97, v91, v91
	v_add_f32_e32 v82, v82, v83
	v_add_f32_e32 v83, v84, v85
	v_fmac_f32_e32 v94, v86, v86
	v_fmac_f32_e32 v95, v88, v88
	v_fmac_f32_e32 v96, v92, v92
	v_fmac_f32_e32 v97, v90, v90
	v_add_f32_e32 v82, v82, v83
	v_add_f32_e32 v83, v94, v95
	v_add_f32_e32 v84, v96, v97
	v_add_f32_e32 v83, v83, v84
	v_add_f32_e32 v82, v100, v82
	v_add_f32_e32 v85, v101, v83
	ds_bpermute_b32 v84, v122, v82
	ds_bpermute_b32 v94, v122, v85
	v_cvt_pk_bf16_f32 v86, v86, v87
	v_cvt_pk_bf16_f32 v87, v88, v89
	v_cvt_pk_bf16_f32 v88, v92, v93
	s_waitcnt lgkmcnt(1)
	v_add_f32_e32 v82, v82, v84
	s_waitcnt lgkmcnt(0)
	v_add_f32_e32 v84, v85, v94
	ds_bpermute_b32 v83, v116, v82
	ds_bpermute_b32 v85, v116, v84
	v_cvt_pk_bf16_f32 v89, v90, v91
	global_store_dwordx4 v[108:109], v[86:89], off offset:256
	s_and_saveexec_b64 s[42:43], s[6:7]
	s_waitcnt lgkmcnt(1)
	v_add_f32_e32 v82, v82, v83
	s_waitcnt lgkmcnt(0)
	v_add_f32_e32 v83, v84, v85
	v_lshl_add_u64 v[86:87], v[190:191], 3, v[138:139]
	v_cndmask_b32_e64 v82, v83, v82, s[8:9]
	global_atomic_add_f32 v[86:87], v82, off
.LBB0_486:
	s_or_b64 exec, exec, s[42:43]
	v_add_u32_e32 v190, 0x80, v182
	v_ashrrev_i32_e32 v191, 31, v190
	v_lshlrev_b64 v[184:185], 11, v[190:191]
	v_lshl_add_u64 v[192:193], v[184:185], 0, v[180:181]
	v_lshl_add_u64 v[194:195], v[192:193], 2, s[46:47]
	global_load_dwordx4 v[196:199], v[194:195], off
	global_load_dwordx4 v[200:203], v[194:195], off offset:16
	global_load_dwordx4 v[206:209], v[194:195], off offset:512
	global_load_dwordx4 v[230:233], v[194:195], off offset:528
	s_waitcnt lgkmcnt(1)
	s_waitcnt lgkmcnt(0)
	v_lshl_add_u64 v[92:93], v[188:189], 1, s[16:17]
	s_waitcnt vmcnt(10)
	v_pk_fma_f32 v[86:87], v[214:215], s[30:31], v[80:81] op_sel_hi:[1,0,1]
	v_pk_fma_f32 v[84:85], v[212:213], s[30:31], v[78:79] op_sel_hi:[1,0,1]
	s_waitcnt vmcnt(9)
	v_pk_fma_f32 v[90:91], v[218:219], s[30:31], v[76:77] op_sel_hi:[1,0,1]
	v_pk_fma_f32 v[88:89], v[216:217], s[30:31], v[74:75] op_sel_hi:[1,0,1]
	v_cvt_pk_bf16_f32 v74, v84, v85
	v_cvt_pk_bf16_f32 v75, v86, v87
	v_add_f32_e32 v97, v90, v91
	v_cvt_pk_bf16_f32 v76, v88, v89
	v_cvt_pk_bf16_f32 v77, v90, v91
	global_store_dwordx4 v[92:93], v[74:77], off
	s_nop 0
	s_nop 0
	s_nop 0
	v_add_f32_e32 v94, v84, v85
	v_add_f32_e32 v95, v86, v87
	v_add_f32_e32 v96, v88, v89
	v_mul_f32_e32 v85, v85, v85
	v_mul_f32_e32 v87, v87, v87
	v_mul_f32_e32 v89, v89, v89
	v_mul_f32_e32 v91, v91, v91
	v_add_f32_e32 v94, v94, v95
	v_add_f32_e32 v95, v96, v97
	v_fmac_f32_e32 v85, v84, v84
	v_fmac_f32_e32 v87, v86, v86
	v_fmac_f32_e32 v89, v88, v88
	v_fmac_f32_e32 v91, v90, v90
	v_add_f32_e32 v84, v94, v95
	v_add_f32_e32 v85, v85, v87
	v_add_f32_e32 v86, v89, v91
	v_add_f32_e32 v84, 0, v84
	v_add_f32_e32 v85, v85, v86
	s_waitcnt vmcnt(9)
	v_pk_fma_f32 v[72:73], v[224:225], s[30:31], v[72:73] op_sel_hi:[1,0,1]
	v_pk_fma_f32 v[70:71], v[222:223], s[30:31], v[70:71] op_sel_hi:[1,0,1]
	s_waitcnt vmcnt(8)
	v_pk_fma_f32 v[74:75], v[228:229], s[30:31], v[68:69] op_sel_hi:[1,0,1]
	v_pk_fma_f32 v[76:77], v[226:227], s[30:31], v[66:67] op_sel_hi:[1,0,1]
	v_add_f32_e32 v66, v70, v71
	v_add_f32_e32 v67, v72, v73
	v_add_f32_e32 v68, v76, v77
	v_add_f32_e32 v69, v74, v75
	v_mul_f32_e32 v78, v71, v71
	v_mul_f32_e32 v79, v73, v73
	v_mul_f32_e32 v80, v77, v77
	v_mul_f32_e32 v81, v75, v75
	v_add_f32_e32 v66, v66, v67
	v_add_f32_e32 v67, v68, v69
	v_fmac_f32_e32 v78, v70, v70
	v_fmac_f32_e32 v79, v72, v72
	v_fmac_f32_e32 v80, v76, v76
	v_fmac_f32_e32 v81, v74, v74
	v_add_f32_e32 v66, v66, v67
	v_add_f32_e32 v67, v78, v79
	v_add_f32_e32 v68, v80, v81
	v_add_f32_e32 v67, v67, v68
	v_add_f32_e32 v66, v84, v66
	v_add_f32_e32 v69, v85, v67
	ds_bpermute_b32 v68, v122, v66
	ds_bpermute_b32 v78, v122, v69
	v_cvt_pk_bf16_f32 v70, v70, v71
	v_cvt_pk_bf16_f32 v71, v72, v73
	v_cvt_pk_bf16_f32 v72, v76, v77
	s_waitcnt lgkmcnt(1)
	v_add_f32_e32 v66, v66, v68
	s_waitcnt lgkmcnt(0)
	v_add_f32_e32 v68, v69, v78
	ds_bpermute_b32 v67, v116, v66
	ds_bpermute_b32 v69, v116, v68
	v_cvt_pk_bf16_f32 v73, v74, v75
	global_store_dwordx4 v[92:93], v[70:73], off offset:256
	s_and_saveexec_b64 s[42:43], s[6:7]
	s_waitcnt lgkmcnt(1)
	v_add_f32_e32 v66, v66, v67
	s_waitcnt lgkmcnt(0)
	v_add_f32_e32 v67, v68, v69
	v_lshl_add_u64 v[70:71], v[186:187], 3, v[138:139]
	v_cndmask_b32_e64 v66, v67, v66, s[8:9]
	global_atomic_add_f32 v[70:71], v66, off
.LBB0_488:
	s_or_b64 exec, exec, s[42:43]
	v_add_u32_e32 v186, 0x90, v182
	v_ashrrev_i32_e32 v187, 31, v186
	v_lshlrev_b64 v[184:185], 11, v[186:187]
	v_lshl_add_u64 v[188:189], v[184:185], 0, v[180:181]
	v_lshl_add_u64 v[194:195], v[188:189], 2, s[46:47]
	global_load_dwordx4 v[212:215], v[194:195], off
	global_load_dwordx4 v[216:219], v[194:195], off offset:16
	global_load_dwordx4 v[222:225], v[194:195], off offset:512
	global_load_dwordx4 v[226:229], v[194:195], off offset:528
	s_waitcnt lgkmcnt(1)
	s_waitcnt lgkmcnt(0)
	v_lshl_add_u64 v[76:77], v[192:193], 1, s[16:17]
	s_waitcnt vmcnt(10)
	v_pk_fma_f32 v[70:71], v[198:199], s[30:31], v[64:65] op_sel_hi:[1,0,1]
	v_pk_fma_f32 v[68:69], v[196:197], s[30:31], v[62:63] op_sel_hi:[1,0,1]
	s_waitcnt vmcnt(9)
	v_pk_fma_f32 v[74:75], v[202:203], s[30:31], v[60:61] op_sel_hi:[1,0,1]
	v_pk_fma_f32 v[72:73], v[200:201], s[30:31], v[58:59] op_sel_hi:[1,0,1]
	v_cvt_pk_bf16_f32 v58, v68, v69
	v_cvt_pk_bf16_f32 v59, v70, v71
	v_add_f32_e32 v81, v74, v75
	v_cvt_pk_bf16_f32 v60, v72, v73
	v_cvt_pk_bf16_f32 v61, v74, v75
	global_store_dwordx4 v[76:77], v[58:61], off
	s_nop 0
	s_nop 0
	s_nop 0
	v_add_f32_e32 v78, v68, v69
	v_add_f32_e32 v79, v70, v71
	v_add_f32_e32 v80, v72, v73
	v_mul_f32_e32 v69, v69, v69
	v_mul_f32_e32 v71, v71, v71
	v_mul_f32_e32 v73, v73, v73
	v_mul_f32_e32 v75, v75, v75
	v_add_f32_e32 v78, v78, v79
	v_add_f32_e32 v79, v80, v81
	v_fmac_f32_e32 v69, v68, v68
	v_fmac_f32_e32 v71, v70, v70
	v_fmac_f32_e32 v73, v72, v72
	v_fmac_f32_e32 v75, v74, v74
	v_add_f32_e32 v68, v78, v79
	v_add_f32_e32 v69, v69, v71
	v_add_f32_e32 v70, v73, v75
	v_add_f32_e32 v68, 0, v68
	v_add_f32_e32 v69, v69, v70
	s_waitcnt vmcnt(9)
	v_pk_fma_f32 v[56:57], v[208:209], s[30:31], v[56:57] op_sel_hi:[1,0,1]
	v_pk_fma_f32 v[54:55], v[206:207], s[30:31], v[54:55] op_sel_hi:[1,0,1]
	s_waitcnt vmcnt(8)
	v_pk_fma_f32 v[58:59], v[232:233], s[30:31], v[52:53] op_sel_hi:[1,0,1]
	v_pk_fma_f32 v[60:61], v[230:231], s[30:31], v[50:51] op_sel_hi:[1,0,1]
	v_add_f32_e32 v50, v54, v55
	v_add_f32_e32 v51, v56, v57
	v_add_f32_e32 v52, v60, v61
	v_add_f32_e32 v53, v58, v59
	v_mul_f32_e32 v62, v55, v55
	v_mul_f32_e32 v63, v57, v57
	v_mul_f32_e32 v64, v61, v61
	v_mul_f32_e32 v65, v59, v59
	v_add_f32_e32 v50, v50, v51
	v_add_f32_e32 v51, v52, v53
	v_fmac_f32_e32 v62, v54, v54
	v_fmac_f32_e32 v63, v56, v56
	v_fmac_f32_e32 v64, v60, v60
	v_fmac_f32_e32 v65, v58, v58
	v_add_f32_e32 v50, v50, v51
	v_add_f32_e32 v51, v62, v63
	v_add_f32_e32 v52, v64, v65
	v_add_f32_e32 v51, v51, v52
	v_add_f32_e32 v50, v68, v50
	v_add_f32_e32 v53, v69, v51
	ds_bpermute_b32 v52, v122, v50
	ds_bpermute_b32 v62, v122, v53
	v_cvt_pk_bf16_f32 v54, v54, v55
	v_cvt_pk_bf16_f32 v55, v56, v57
	v_cvt_pk_bf16_f32 v56, v60, v61
	s_waitcnt lgkmcnt(1)
	v_add_f32_e32 v50, v50, v52
	s_waitcnt lgkmcnt(0)
	v_add_f32_e32 v52, v53, v62
	ds_bpermute_b32 v51, v116, v50
	ds_bpermute_b32 v53, v116, v52
	v_cvt_pk_bf16_f32 v57, v58, v59
	global_store_dwordx4 v[76:77], v[54:57], off offset:256
	s_and_saveexec_b64 s[42:43], s[6:7]
	s_waitcnt lgkmcnt(1)
	v_add_f32_e32 v50, v50, v51
	s_waitcnt lgkmcnt(0)
	v_add_f32_e32 v51, v52, v53
	v_lshl_add_u64 v[54:55], v[190:191], 3, v[138:139]
	v_cndmask_b32_e64 v50, v51, v50, s[8:9]
	global_atomic_add_f32 v[54:55], v50, off
.LBB0_490:
	s_or_b64 exec, exec, s[42:43]
	v_add_u32_e32 v190, 0xa0, v182
	v_ashrrev_i32_e32 v191, 31, v190
	v_lshlrev_b64 v[184:185], 11, v[190:191]
	v_lshl_add_u64 v[192:193], v[184:185], 0, v[180:181]
	v_lshl_add_u64 v[194:195], v[192:193], 2, s[46:47]
	global_load_dwordx4 v[196:199], v[194:195], off
	global_load_dwordx4 v[200:203], v[194:195], off offset:16
	global_load_dwordx4 v[206:209], v[194:195], off offset:512
	global_load_dwordx4 v[230:233], v[194:195], off offset:528
	s_waitcnt lgkmcnt(1)
	s_waitcnt lgkmcnt(0)
	v_lshl_add_u64 v[60:61], v[188:189], 1, s[16:17]
	s_waitcnt vmcnt(10)
	v_pk_fma_f32 v[54:55], v[214:215], s[30:31], v[48:49] op_sel_hi:[1,0,1]
	v_pk_fma_f32 v[52:53], v[212:213], s[30:31], v[46:47] op_sel_hi:[1,0,1]
	s_waitcnt vmcnt(9)
	v_pk_fma_f32 v[58:59], v[218:219], s[30:31], v[44:45] op_sel_hi:[1,0,1]
	v_pk_fma_f32 v[56:57], v[216:217], s[30:31], v[42:43] op_sel_hi:[1,0,1]
	v_cvt_pk_bf16_f32 v42, v52, v53
	v_cvt_pk_bf16_f32 v43, v54, v55
	v_add_f32_e32 v65, v58, v59
	v_cvt_pk_bf16_f32 v44, v56, v57
	v_cvt_pk_bf16_f32 v45, v58, v59
	global_store_dwordx4 v[60:61], v[42:45], off
	s_nop 0
	s_nop 0
	s_nop 0
	v_add_f32_e32 v62, v52, v53
	v_add_f32_e32 v63, v54, v55
	v_add_f32_e32 v64, v56, v57
	v_mul_f32_e32 v53, v53, v53
	v_mul_f32_e32 v55, v55, v55
	v_mul_f32_e32 v57, v57, v57
	v_mul_f32_e32 v59, v59, v59
	v_add_f32_e32 v62, v62, v63
	v_add_f32_e32 v63, v64, v65
	v_fmac_f32_e32 v53, v52, v52
	v_fmac_f32_e32 v55, v54, v54
	v_fmac_f32_e32 v57, v56, v56
	v_fmac_f32_e32 v59, v58, v58
	v_add_f32_e32 v52, v62, v63
	v_add_f32_e32 v53, v53, v55
	v_add_f32_e32 v54, v57, v59
	v_add_f32_e32 v52, 0, v52
	v_add_f32_e32 v53, v53, v54
	s_waitcnt vmcnt(9)
	v_pk_fma_f32 v[40:41], v[224:225], s[30:31], v[40:41] op_sel_hi:[1,0,1]
	v_pk_fma_f32 v[38:39], v[222:223], s[30:31], v[38:39] op_sel_hi:[1,0,1]
	s_waitcnt vmcnt(8)
	v_pk_fma_f32 v[42:43], v[228:229], s[30:31], v[36:37] op_sel_hi:[1,0,1]
	v_pk_fma_f32 v[44:45], v[226:227], s[30:31], v[34:35] op_sel_hi:[1,0,1]
	v_add_f32_e32 v34, v38, v39
	v_add_f32_e32 v35, v40, v41
	v_add_f32_e32 v36, v44, v45
	v_add_f32_e32 v37, v42, v43
	v_mul_f32_e32 v46, v39, v39
	v_mul_f32_e32 v47, v41, v41
	v_mul_f32_e32 v48, v45, v45
	v_mul_f32_e32 v49, v43, v43
	v_add_f32_e32 v34, v34, v35
	v_add_f32_e32 v35, v36, v37
	v_fmac_f32_e32 v46, v38, v38
	v_fmac_f32_e32 v47, v40, v40
	v_fmac_f32_e32 v48, v44, v44
	v_fmac_f32_e32 v49, v42, v42
	v_add_f32_e32 v34, v34, v35
	v_add_f32_e32 v35, v46, v47
	v_add_f32_e32 v36, v48, v49
	v_add_f32_e32 v35, v35, v36
	v_add_f32_e32 v34, v52, v34
	v_add_f32_e32 v37, v53, v35
	ds_bpermute_b32 v36, v122, v34
	ds_bpermute_b32 v46, v122, v37
	v_cvt_pk_bf16_f32 v38, v38, v39
	v_cvt_pk_bf16_f32 v39, v40, v41
	v_cvt_pk_bf16_f32 v40, v44, v45
	s_waitcnt lgkmcnt(1)
	v_add_f32_e32 v34, v34, v36
	s_waitcnt lgkmcnt(0)
	v_add_f32_e32 v36, v37, v46
	ds_bpermute_b32 v35, v116, v34
	ds_bpermute_b32 v37, v116, v36
	v_cvt_pk_bf16_f32 v41, v42, v43
	global_store_dwordx4 v[60:61], v[38:41], off offset:256
	s_and_saveexec_b64 s[42:43], s[6:7]
	s_waitcnt lgkmcnt(1)
	v_add_f32_e32 v34, v34, v35
	s_waitcnt lgkmcnt(0)
	v_add_f32_e32 v35, v36, v37
	v_lshl_add_u64 v[38:39], v[186:187], 3, v[138:139]
	v_cndmask_b32_e64 v34, v35, v34, s[8:9]
	global_atomic_add_f32 v[38:39], v34, off
.LBB0_492:
	s_or_b64 exec, exec, s[42:43]
	v_add_u32_e32 v186, 0xb0, v182
	v_ashrrev_i32_e32 v187, 31, v186
	v_lshlrev_b64 v[184:185], 11, v[186:187]
	v_lshl_add_u64 v[188:189], v[184:185], 0, v[180:181]
	v_lshl_add_u64 v[182:183], v[188:189], 2, s[46:47]
	global_load_dwordx4 v[212:215], v[182:183], off
	global_load_dwordx4 v[216:219], v[182:183], off offset:16
	global_load_dwordx4 v[222:225], v[182:183], off offset:512
	global_load_dwordx4 v[226:229], v[182:183], off offset:528
	s_waitcnt lgkmcnt(1)
	s_waitcnt lgkmcnt(0)
	v_lshl_add_u64 v[44:45], v[192:193], 1, s[16:17]
	s_waitcnt vmcnt(10)
	v_pk_fma_f32 v[38:39], v[198:199], s[30:31], v[32:33] op_sel_hi:[1,0,1]
	v_pk_fma_f32 v[36:37], v[196:197], s[30:31], v[30:31] op_sel_hi:[1,0,1]
	s_waitcnt vmcnt(9)
	v_pk_fma_f32 v[42:43], v[202:203], s[30:31], v[28:29] op_sel_hi:[1,0,1]
	v_pk_fma_f32 v[40:41], v[200:201], s[30:31], v[26:27] op_sel_hi:[1,0,1]
	v_cvt_pk_bf16_f32 v26, v36, v37
	v_cvt_pk_bf16_f32 v27, v38, v39
	v_add_f32_e32 v49, v42, v43
	v_cvt_pk_bf16_f32 v28, v40, v41
	v_cvt_pk_bf16_f32 v29, v42, v43
	global_store_dwordx4 v[44:45], v[26:29], off
	s_nop 0
	s_nop 0
	s_nop 0
	v_add_f32_e32 v46, v36, v37
	v_add_f32_e32 v47, v38, v39
	v_add_f32_e32 v48, v40, v41
	v_mul_f32_e32 v37, v37, v37
	v_mul_f32_e32 v39, v39, v39
	v_mul_f32_e32 v41, v41, v41
	v_mul_f32_e32 v43, v43, v43
	v_add_f32_e32 v46, v46, v47
	v_add_f32_e32 v47, v48, v49
	v_fmac_f32_e32 v37, v36, v36
	v_fmac_f32_e32 v39, v38, v38
	v_fmac_f32_e32 v41, v40, v40
	v_fmac_f32_e32 v43, v42, v42
	v_add_f32_e32 v36, v46, v47
	v_add_f32_e32 v37, v37, v39
	v_add_f32_e32 v38, v41, v43
	v_add_f32_e32 v36, 0, v36
	v_add_f32_e32 v37, v37, v38
	s_waitcnt vmcnt(9)
	v_pk_fma_f32 v[24:25], v[208:209], s[30:31], v[24:25] op_sel_hi:[1,0,1]
	v_pk_fma_f32 v[22:23], v[206:207], s[30:31], v[22:23] op_sel_hi:[1,0,1]
	s_waitcnt vmcnt(8)
	v_pk_fma_f32 v[26:27], v[232:233], s[30:31], v[20:21] op_sel_hi:[1,0,1]
	v_pk_fma_f32 v[28:29], v[230:231], s[30:31], v[18:19] op_sel_hi:[1,0,1]
	v_add_f32_e32 v18, v22, v23
	v_add_f32_e32 v19, v24, v25
	v_add_f32_e32 v20, v28, v29
	v_add_f32_e32 v21, v26, v27
	v_mul_f32_e32 v30, v23, v23
	v_mul_f32_e32 v31, v25, v25
	v_mul_f32_e32 v32, v29, v29
	v_mul_f32_e32 v33, v27, v27
	v_add_f32_e32 v18, v18, v19
	v_add_f32_e32 v19, v20, v21
	v_fmac_f32_e32 v30, v22, v22
	v_fmac_f32_e32 v31, v24, v24
	v_fmac_f32_e32 v32, v28, v28
	v_fmac_f32_e32 v33, v26, v26
	v_add_f32_e32 v18, v18, v19
	v_add_f32_e32 v19, v30, v31
	v_add_f32_e32 v20, v32, v33
	v_add_f32_e32 v19, v19, v20
	v_add_f32_e32 v18, v36, v18
	v_add_f32_e32 v21, v37, v19
	ds_bpermute_b32 v20, v122, v18
	ds_bpermute_b32 v30, v122, v21
	v_cvt_pk_bf16_f32 v22, v22, v23
	v_cvt_pk_bf16_f32 v23, v24, v25
	v_cvt_pk_bf16_f32 v24, v28, v29
	s_waitcnt lgkmcnt(1)
	v_add_f32_e32 v18, v18, v20
	s_waitcnt lgkmcnt(0)
	v_add_f32_e32 v20, v21, v30
	ds_bpermute_b32 v19, v116, v18
	ds_bpermute_b32 v21, v116, v20
	v_cvt_pk_bf16_f32 v25, v26, v27
	global_store_dwordx4 v[44:45], v[22:25], off offset:256
	s_and_saveexec_b64 s[42:43], s[6:7]
	s_waitcnt lgkmcnt(1)
	v_add_f32_e32 v18, v18, v19
	s_waitcnt lgkmcnt(0)
	v_add_f32_e32 v19, v20, v21
	v_lshl_add_u64 v[22:23], v[190:191], 3, v[138:139]
	v_cndmask_b32_e64 v18, v19, v18, s[8:9]
	global_atomic_add_f32 v[22:23], v18, off
.LBB0_494:
	s_or_b64 exec, exec, s[42:43]
	s_waitcnt lgkmcnt(1)
	s_waitcnt lgkmcnt(0)
	s_nop 4
	v_lshl_add_u64 v[28:29], v[188:189], 1, s[16:17]
	s_waitcnt vmcnt(6)
	v_pk_fma_f32 v[22:23], v[214:215], s[30:31], v[16:17] op_sel_hi:[1,0,1]
	v_pk_fma_f32 v[20:21], v[212:213], s[30:31], v[14:15] op_sel_hi:[1,0,1]
	s_waitcnt vmcnt(5)
	v_pk_fma_f32 v[26:27], v[218:219], s[30:31], v[12:13] op_sel_hi:[1,0,1]
	v_pk_fma_f32 v[24:25], v[216:217], s[30:31], v[10:11] op_sel_hi:[1,0,1]
	v_cvt_pk_bf16_f32 v10, v20, v21
	v_cvt_pk_bf16_f32 v11, v22, v23
	v_add_f32_e32 v33, v26, v27
	v_cvt_pk_bf16_f32 v12, v24, v25
	v_cvt_pk_bf16_f32 v13, v26, v27
	global_store_dwordx4 v[28:29], v[10:13], off
	s_nop 0
	s_nop 0
	s_nop 0
	v_add_f32_e32 v30, v20, v21
	v_add_f32_e32 v31, v22, v23
	v_add_f32_e32 v32, v24, v25
	v_mul_f32_e32 v21, v21, v21
	v_mul_f32_e32 v23, v23, v23
	v_mul_f32_e32 v25, v25, v25
	v_mul_f32_e32 v27, v27, v27
	v_add_f32_e32 v30, v30, v31
	v_add_f32_e32 v31, v32, v33
	v_fmac_f32_e32 v21, v20, v20
	v_fmac_f32_e32 v23, v22, v22
	v_fmac_f32_e32 v25, v24, v24
	v_fmac_f32_e32 v27, v26, v26
	v_add_f32_e32 v20, v30, v31
	v_add_f32_e32 v21, v21, v23
	v_add_f32_e32 v22, v25, v27
	v_add_f32_e32 v20, 0, v20
	v_add_f32_e32 v21, v21, v22
	s_waitcnt vmcnt(5)
	v_pk_fma_f32 v[8:9], v[224:225], s[30:31], v[8:9] op_sel_hi:[1,0,1]
	v_pk_fma_f32 v[6:7], v[222:223], s[30:31], v[6:7] op_sel_hi:[1,0,1]
	s_waitcnt vmcnt(4)
	v_pk_fma_f32 v[10:11], v[228:229], s[30:31], v[4:5] op_sel_hi:[1,0,1]
	v_pk_fma_f32 v[12:13], v[226:227], s[30:31], v[2:3] op_sel_hi:[1,0,1]
	v_add_f32_e32 v2, v6, v7
	v_add_f32_e32 v3, v8, v9
	v_add_f32_e32 v4, v12, v13
	v_add_f32_e32 v5, v10, v11
	v_mul_f32_e32 v14, v7, v7
	v_mul_f32_e32 v15, v9, v9
	v_mul_f32_e32 v16, v13, v13
	v_mul_f32_e32 v17, v11, v11
	v_add_f32_e32 v2, v2, v3
	v_add_f32_e32 v3, v4, v5
	v_fmac_f32_e32 v14, v6, v6
	v_fmac_f32_e32 v15, v8, v8
	v_fmac_f32_e32 v16, v12, v12
	v_fmac_f32_e32 v17, v10, v10
	v_add_f32_e32 v2, v2, v3
	v_add_f32_e32 v3, v14, v15
	v_add_f32_e32 v4, v16, v17
	v_add_f32_e32 v3, v3, v4
	v_add_f32_e32 v2, v20, v2
	v_add_f32_e32 v5, v21, v3
	ds_bpermute_b32 v4, v122, v2
	ds_bpermute_b32 v14, v122, v5
	v_cvt_pk_bf16_f32 v6, v6, v7
	v_cvt_pk_bf16_f32 v7, v8, v9
	v_cvt_pk_bf16_f32 v8, v12, v13
	s_waitcnt lgkmcnt(1)
	v_add_f32_e32 v2, v2, v4
	s_waitcnt lgkmcnt(0)
	v_add_f32_e32 v4, v5, v14
	ds_bpermute_b32 v3, v116, v2
	ds_bpermute_b32 v5, v116, v4
	v_cvt_pk_bf16_f32 v9, v10, v11
	global_store_dwordx4 v[28:29], v[6:9], off offset:256
	s_and_saveexec_b64 s[42:43], s[6:7]
	s_waitcnt lgkmcnt(1)
	v_add_f32_e32 v2, v2, v3
	s_waitcnt lgkmcnt(0)
	v_add_f32_e32 v3, v4, v5
	v_lshl_add_u64 v[6:7], v[186:187], 3, v[138:139]
	v_cndmask_b32_e64 v2, v3, v2, s[8:9]
	global_atomic_add_f32 v[6:7], v2, off
